# rglru item: the 11 conv-window row loads issued together (were one load plus a full wait each)
# speedup vs baseline: 1.0058x; 1.0058x over previous
.LBB0_578:
	s_waitcnt vmcnt(7)
	v_bfrev_b32_e32 v0, 4.0
	v_sub_co_u32_e32 v0, vcc, s81, v0
	s_and_b64 s[10:11], vcc, exec
	v_readfirstlane_b32 s4, v0
	s_cselect_b32 s4, s81, s4
	s_and_b32 s13, s4, 1
	s_ashr_i32 s44, s4, 6
	s_ashr_i32 s4, s4, 1
	s_mov_b64 s[10:11], s[0:1]
	s_cmpk_eq_i32 s4, 0x80
	s_cselect_b64 s[34:35], -1, 0
	s_cmpk_lg_i32 s4, 0x80
	s_load_dwordx4 s[28:31], s[10:11], 0x20
	s_load_dwordx4 s[20:23], s[10:11], 0x48
	s_load_dwordx4 s[36:39], s[10:11], 0xc8
	s_load_dwordx2 s[48:49], s[10:11], 0x60
	s_load_dwordx4 s[24:27], s[10:11], 0x70
	s_cselect_b64 s[42:43], -1, 0
	s_and_b32 s17, s4, 31
	s_ashr_i32 s45, s44, 31
	v_mov_b32_e32 v68, v236
	s_lshl_b32 s12, s17, 7
	s_lshl_b64 s[40:41], s[44:45], 12
	s_waitcnt lgkmcnt(0)
	s_add_u32 s46, s38, 0x82b0000
	v_and_b32_e32 v70, 31, v68
	v_lshl_or_b32 v69, s13, 5, v70
	s_addc_u32 s47, s39, 0
	s_lshl_b64 s[10:11], s[84:85], 2
	v_lshlrev_b32_e32 v174, 4, v69
	s_add_u32 s10, s22, s10
	s_waitcnt vmcnt(6)
	v_lshl_add_u64 v[4:5], s[20:21], 0, v[174:175]
	s_addc_u32 s11, s23, s11
	s_waitcnt vmcnt(0)
	v_lshl_add_u64 v[16:17], s[90:91], 2, v[4:5]
	global_load_dwordx4 v[0:3], v174, s[10:11]
	global_load_dwordx4 v[4:7], v[16:17], off
	global_load_dwordx4 v[8:11], v[16:17], off offset:1024
	global_load_dwordx4 v[12:15], v[16:17], off offset:2048
	s_nop 0
	global_load_dwordx4 v[16:19], v[16:17], off offset:3072
	v_ashrrev_i32_e32 v72, 5, v68
	v_readfirstlane_b32 s16, v68
	s_mov_b64 s[10:11], -1
	s_and_b64 vcc, exec, s[42:43]
	v_lshlrev_b32_e32 v71, 3, v72
	s_cbranch_vccz .LBB0_604
	v_add3_u32 v46, s12, -3, v71
	s_waitcnt vmcnt(7)
	v_lshlrev_b32_e32 v20, 3, v69
	v_mov_b32_e32 v21, v175
	v_lshl_add_u64 v[44:45], s[46:47], 0, v[20:21]
	s_waitcnt vmcnt(5)
	v_ashrrev_i32_e32 v47, 31, v46
	v_lshl_add_u64 v[20:21], s[40:41], 0, v[46:47]
	v_mad_u64_u32 v[158:159], s[20:21], v20, s18, v[44:45]
	v_mad_i32_i24 v159, v21, s18, v159
	s_mov_b64 s[22:23], 0x1200
	v_lshl_add_u64 v[152:153], v[158:159], 0, s[22:23]
	s_mov_b64 s[22:23], 0x2400
	v_lshl_add_u64 v[154:155], v[158:159], 0, s[22:23]
	s_mov_b64 s[22:23], 0x3600
	v_lshl_add_u64 v[156:157], v[158:159], 0, s[22:23]
	v_mov_b32_e32 v36, 0
	v_mov_b32_e32 v37, 0
	v_mov_b32_e32 v40, 0
	v_mov_b32_e32 v41, 0
	v_mov_b32_e32 v32, 0
	v_mov_b32_e32 v33, 0
	v_mov_b32_e32 v38, 0
	v_mov_b32_e32 v39, 0
	v_mov_b32_e32 v42, 0
	v_mov_b32_e32 v43, 0
	v_mov_b32_e32 v48, 0
	v_mov_b32_e32 v49, 0
	v_cmp_lt_i32_e32 vcc, -1, v46
	s_and_saveexec_b64 s[10:11], vcc
	global_load_dwordx2 v[130:131], v[158:159], off
	s_mov_b64 exec, s[10:11]
	v_cmp_lt_i32_e32 vcc, -2, v46
	s_and_saveexec_b64 s[10:11], vcc
	global_load_dwordx2 v[132:133], v[158:159], off offset:1536
	s_mov_b64 exec, s[10:11]
	v_cmp_lt_i32_e32 vcc, -3, v46
	s_and_saveexec_b64 s[10:11], vcc
	global_load_dwordx2 v[134:135], v[158:159], off offset:3072
	s_mov_b64 exec, s[10:11]
	global_load_dwordx2 v[136:137], v[152:153], off
	global_load_dwordx2 v[138:139], v[152:153], off offset:1536
	global_load_dwordx2 v[140:141], v[152:153], off offset:3072
	global_load_dwordx2 v[142:143], v[154:155], off
	global_load_dwordx2 v[144:145], v[154:155], off offset:1536
	global_load_dwordx2 v[146:147], v[154:155], off offset:3072
	global_load_dwordx2 v[148:149], v[156:157], off
	global_load_dwordx2 v[150:151], v[156:157], off offset:1536
	s_waitcnt vmcnt(0)
	v_lshlrev_b32_e32 v34, 16, v136
	v_and_b32_e32 v35, 0xffff0000, v136
	v_lshlrev_b32_e32 v52, 16, v137
	v_and_b32_e32 v53, 0xffff0000, v137
	v_lshlrev_b32_e32 v54, 16, v138
	v_and_b32_e32 v55, 0xffff0000, v138
	v_lshlrev_b32_e32 v56, 16, v139
	v_and_b32_e32 v57, 0xffff0000, v139
	v_lshlrev_b32_e32 v50, 16, v140
	v_and_b32_e32 v51, 0xffff0000, v140
	v_lshlrev_b32_e32 v60, 16, v141
	v_and_b32_e32 v61, 0xffff0000, v141
	v_lshlrev_b32_e32 v62, 16, v142
	v_and_b32_e32 v63, 0xffff0000, v142
	v_lshlrev_b32_e32 v64, 16, v143
	v_and_b32_e32 v65, 0xffff0000, v143
	v_lshlrev_b32_e32 v58, 16, v144
	v_and_b32_e32 v59, 0xffff0000, v144
	v_lshlrev_b32_e32 v66, 16, v145
	v_and_b32_e32 v67, 0xffff0000, v145
	v_lshlrev_b32_e32 v24, 16, v146
	v_and_b32_e32 v25, 0xffff0000, v146
	v_lshlrev_b32_e32 v26, 16, v147
	v_and_b32_e32 v27, 0xffff0000, v147
	v_lshlrev_b32_e32 v20, 16, v148
	v_and_b32_e32 v21, 0xffff0000, v148
	v_lshlrev_b32_e32 v22, 16, v149
	v_and_b32_e32 v23, 0xffff0000, v149
	v_lshlrev_b32_e32 v28, 16, v150
	v_and_b32_e32 v29, 0xffff0000, v150
	v_lshlrev_b32_e32 v30, 16, v151
	v_and_b32_e32 v31, 0xffff0000, v151
	v_cmp_lt_i32_e32 vcc, -1, v46
	s_and_saveexec_b64 s[10:11], vcc
	v_lshlrev_b32_e32 v36, 16, v130
	v_and_b32_e32 v37, 0xffff0000, v130
	v_lshlrev_b32_e32 v40, 16, v131
	v_and_b32_e32 v41, 0xffff0000, v131
	s_mov_b64 exec, s[10:11]
	v_cmp_lt_i32_e32 vcc, -2, v46
	s_and_saveexec_b64 s[10:11], vcc
	v_lshlrev_b32_e32 v32, 16, v132
	v_and_b32_e32 v33, 0xffff0000, v132
	v_lshlrev_b32_e32 v38, 16, v133
	v_and_b32_e32 v39, 0xffff0000, v133
	s_mov_b64 exec, s[10:11]
	v_cmp_lt_i32_e32 vcc, -3, v46
	s_and_saveexec_b64 s[10:11], vcc
	v_lshlrev_b32_e32 v42, 16, v134
	v_and_b32_e32 v43, 0xffff0000, v134
	v_lshlrev_b32_e32 v48, 16, v135
	v_and_b32_e32 v49, 0xffff0000, v135
	s_mov_b64 exec, s[10:11]
	s_waitcnt vmcnt(3)
	v_pk_fma_f32 v[36:37], v[4:5], v[36:37], v[0:1]
	v_pk_fma_f32 v[40:41], v[6:7], v[40:41], v[2:3]
	s_waitcnt vmcnt(2)
	v_pk_fma_f32 v[36:37], v[8:9], v[32:33], v[36:37]
	s_cmp_eq_u32 s17, 31
	v_pk_fma_f32 v[40:41], v[10:11], v[38:39], v[40:41]
	s_waitcnt vmcnt(1)
	v_pk_fma_f32 v[36:37], v[12:13], v[42:43], v[36:37]
	s_movk_i32 s17, 0x1080
	v_lshlrev_b32_e32 v73, 4, v70
	v_pk_fma_f32 v[40:41], v[14:15], v[48:49], v[40:41]
	s_waitcnt vmcnt(0)
	v_pk_fma_f32 v[44:45], v[16:17], v[34:35], v[36:37]
	v_mul_lo_u32 v36, v72, s17
	v_pk_fma_f32 v[46:47], v[18:19], v[52:53], v[40:41]
	v_add3_u32 v40, 0, v73, v36
	v_pk_fma_f32 v[36:37], v[6:7], v[38:39], v[2:3]
	v_pk_fma_f32 v[32:33], v[4:5], v[32:33], v[0:1]
	v_pk_fma_f32 v[36:37], v[10:11], v[48:49], v[36:37]
	v_pk_fma_f32 v[32:33], v[8:9], v[42:43], v[32:33]
	v_pk_fma_f32 v[36:37], v[14:15], v[52:53], v[36:37]
	v_pk_fma_f32 v[32:33], v[12:13], v[34:35], v[32:33]
	v_pk_fma_f32 v[38:39], v[18:19], v[56:57], v[36:37]
	v_pk_fma_f32 v[36:37], v[16:17], v[54:55], v[32:33]
	v_pk_fma_f32 v[32:33], v[6:7], v[48:49], v[2:3]
	ds_write_b128 v40, v[36:39] offset:528
	v_pk_fma_f32 v[36:37], v[4:5], v[42:43], v[0:1]
	v_pk_fma_f32 v[32:33], v[10:11], v[52:53], v[32:33]
	v_pk_fma_f32 v[36:37], v[8:9], v[34:35], v[36:37]
	v_pk_fma_f32 v[32:33], v[14:15], v[56:57], v[32:33]
	v_pk_fma_f32 v[36:37], v[12:13], v[54:55], v[36:37]
	v_pk_fma_f32 v[38:39], v[18:19], v[60:61], v[32:33]
	v_pk_fma_f32 v[32:33], v[6:7], v[52:53], v[2:3]
	v_pk_fma_f32 v[34:35], v[4:5], v[34:35], v[0:1]
	v_pk_fma_f32 v[36:37], v[16:17], v[50:51], v[36:37]
	v_pk_fma_f32 v[32:33], v[10:11], v[56:57], v[32:33]
	v_pk_fma_f32 v[34:35], v[8:9], v[54:55], v[34:35]
	ds_write_b128 v40, v[36:39] offset:1056
	v_pk_fma_f32 v[32:33], v[14:15], v[60:61], v[32:33]
	v_pk_fma_f32 v[36:37], v[12:13], v[50:51], v[34:35]
	v_pk_fma_f32 v[34:35], v[18:19], v[64:65], v[32:33]
	v_pk_fma_f32 v[32:33], v[16:17], v[62:63], v[36:37]
	ds_write_b128 v40, v[32:35] offset:1584
	v_pk_fma_f32 v[32:33], v[6:7], v[56:57], v[2:3]
	v_pk_fma_f32 v[34:35], v[4:5], v[54:55], v[0:1]
	v_pk_fma_f32 v[32:33], v[10:11], v[60:61], v[32:33]
	v_pk_fma_f32 v[34:35], v[8:9], v[50:51], v[34:35]
	v_pk_fma_f32 v[32:33], v[14:15], v[64:65], v[32:33]
	v_pk_fma_f32 v[36:37], v[12:13], v[62:63], v[34:35]
	v_pk_fma_f32 v[34:35], v[18:19], v[66:67], v[32:33]
	v_pk_fma_f32 v[32:33], v[16:17], v[58:59], v[36:37]
	ds_write_b128 v40, v[32:35] offset:2112
	v_pk_fma_f32 v[32:33], v[6:7], v[60:61], v[2:3]
	v_pk_fma_f32 v[34:35], v[4:5], v[50:51], v[0:1]
	v_pk_fma_f32 v[32:33], v[10:11], v[64:65], v[32:33]
	v_pk_fma_f32 v[34:35], v[8:9], v[62:63], v[34:35]
	v_pk_fma_f32 v[32:33], v[14:15], v[66:67], v[32:33]
	v_pk_fma_f32 v[36:37], v[12:13], v[58:59], v[34:35]
	v_pk_fma_f32 v[34:35], v[18:19], v[26:27], v[32:33]
	v_pk_fma_f32 v[32:33], v[16:17], v[24:25], v[36:37]
	ds_write_b128 v40, v[32:35] offset:2640
	v_pk_fma_f32 v[32:33], v[6:7], v[64:65], v[2:3]
	v_pk_fma_f32 v[34:35], v[4:5], v[62:63], v[0:1]
	v_pk_fma_f32 v[32:33], v[10:11], v[66:67], v[32:33]
	v_pk_fma_f32 v[34:35], v[8:9], v[58:59], v[34:35]
	v_pk_fma_f32 v[32:33], v[14:15], v[26:27], v[32:33]
	v_pk_fma_f32 v[36:37], v[12:13], v[24:25], v[34:35]
	v_pk_fma_f32 v[34:35], v[18:19], v[22:23], v[32:33]
	v_pk_fma_f32 v[32:33], v[16:17], v[20:21], v[36:37]
	ds_write_b128 v40, v[32:35] offset:3168
	v_pk_fma_f32 v[32:33], v[6:7], v[66:67], v[2:3]
	v_pk_fma_f32 v[34:35], v[4:5], v[58:59], v[0:1]
	v_pk_fma_f32 v[32:33], v[10:11], v[26:27], v[32:33]
	v_pk_fma_f32 v[34:35], v[8:9], v[24:25], v[34:35]
	s_cselect_b64 s[10:11], -1, 0
	v_pk_fma_f32 v[32:33], v[14:15], v[22:23], v[32:33]
	v_pk_fma_f32 v[36:37], v[12:13], v[20:21], v[34:35]
	v_cmp_eq_u32_e32 vcc, 15, v72
	v_pk_fma_f32 v[34:35], v[18:19], v[30:31], v[32:33]
	v_pk_fma_f32 v[32:33], v[16:17], v[28:29], v[36:37]
	s_and_b64 s[20:21], s[10:11], vcc
	ds_write_b128 v40, v[44:47]
	ds_write_b128 v40, v[32:35] offset:3696
	s_and_saveexec_b64 s[10:11], s[20:21]
	s_cbranch_execz .LBB0_603
	s_add_i32 s17, s44, s59
	s_mul_hi_i32 s21, s17, 0xc00
	s_mulk_i32 s17, 0xc00
	s_add_u32 s20, s36, s17
	s_addc_u32 s21, s37, s21
	v_lshl_add_u64 v[32:33], s[20:21], 0, v[174:175]
	s_mov_b64 s[20:21], 0x4182000
	v_lshl_add_u64 v[34:35], v[32:33], 0, s[20:21]
	v_add_co_u32_e32 v32, vcc, 0x4182000, v32
	s_nop 1
	v_addc_co_u32_e32 v33, vcc, 0, v33, vcc
	global_store_dwordx4 v[32:33], v[24:27], off
	global_store_dwordx4 v[34:35], v[20:23], off offset:1024
	global_store_dwordx4 v[34:35], v[28:31], off offset:2048
